# sc1 write-through stores for attention epilogue, P4 state stores, P2b CQN/CKVN stores (less dirty L2 at the global barriers' wbl2)
# baseline (speedup 1.0000x reference)
; __device__ __forceinline__ float bf2f(unsigned short u) { return __uint_as_float((unsigned)u << 16); }
; __device__ __forceinline__ unsigned short f2bf(float f) { unsigned u = __float_as_uint(f); return (unsigned short)((u + 0x7fffu + ((u >> 16) & 1u)) >> 16); }
; __device__ __forceinline__ unsigned pk2(float lo, float hi) { return pg8::cvtpk(lo, hi); }
; __device__ __forceinline__ void p2b_rows(const Params& P, int G) {
;     ...
;     for (int m = blockIdx.x * 8 + wave; m < M; m += G * 8) {
;         const bf16_t* zr = Z + (size_t)m * ZC;
;         const u32x4 a = *(const u32x4*)(zr + ZO_CQ + 8 * lane); const u32x2 k = *(const u32x2*)(zr + ZO_CKV + 4 * lane);
;         float s1 = 0.f, s2 = 0.f;
; #pragma unroll
;         for (int e = 0; e < 4; ++e) { const float lo = __uint_as_float(a[e] << 16), hi = __uint_as_float(a[e] & 0xffff0000u); s1 += lo * lo + hi * hi; }
; #pragma unroll
;         for (int e = 0; e < 2; ++e) { const float lo = __uint_as_float(k[e] << 16), hi = __uint_as_float(k[e] & 0xffff0000u); s2 += lo * lo + hi * hi; }
;         s1 = wave_sum(s1); s2 = wave_sum(s2);
;         const float r1 = rsqrtf(s1 * (1.0f / 512.0f) + RMS_EPS), r2 = rsqrtf(s2 * (1.0f / 256.0f) + RMS_EPS);
;         { u32x4 w;
; #pragma unroll
;           for (int e = 0; e < 4; ++e) w[e] = pk2(__uint_as_float(a[e] << 16) * r1, __uint_as_float(a[e] & 0xffff0000u) * r1);
;           *(u32x4*)(CQN + (size_t)m * 512 + 8 * lane) = w;
;           u32x2 w2;
; #pragma unroll
;           for (int e = 0; e < 2; ++e) w2[e] = pk2(__uint_as_float(k[e] << 16) * r2, __uint_as_float(k[e] & 0xffff0000u) * r2);
;           *(u32x2*)(CKVN + (size_t)m * 256 + 4 * lane) = w2; }
;         if (lane < 32) { const float x1 = bf2f(zr[ZO_KR + lane]), x2 = bf2f(zr[ZO_KR + 32 + lane]); const float c = cs[(size_t)m * 64 + 2 * lane], s = cs[(size_t)m * 64 + 2 * lane + 1];
;             KR[(size_t)m * 64 + lane] = f2bf(x1 * c - x2 * s); KR[(size_t)m * 64 + 32 + lane] = f2bf(x2 * c + x1 * s); }
.LBB0_300:
	s_waitcnt vmcnt(4)
	v_mov_b32_e32 v26, v108
	v_mov_b32_e32 v27, v109
	v_mov_b32_e32 v28, v110
	v_mov_b32_e32 v29, v111
	v_mov_b32_e32 v30, v112
	v_mov_b32_e32 v31, v113
	v_mov_b32_e32 v104, v114
	v_mov_b32_e32 v105, v115
	v_mov_b32_e32 v106, v116
	v_mov_b32_e32 v107, v117
	v_add_u32_e32 v118, s42, v0
	s_and_b32 s4, s2, 7
	s_lshl_b32 s4, s4, 11
	s_addk_i32 s4, 0x7ff
	s_cmpk_eq_u32 s92, 0x100
	s_cselect_b32 s4, s4, 0x3fff
	v_cmp_ge_i32_e32 vcc, s4, v118
	s_and_saveexec_b64 s[6:7], vcc
	v_lshl_add_u64 v[120:121], v[16:17], 0, v[12:13]
	v_lshl_add_u64 v[122:123], v[16:17], 0, v[2:3]
	v_lshl_add_u64 v[100:101], v[16:17], 0, v[4:5]
	s_mov_b64 s[4:5], 0x1000
	v_lshl_add_u64 v[102:103], s[58:59], 0, v[6:7]
	global_load_dwordx4 v[108:111], v[120:121], off
	v_lshl_add_u64 v[100:101], v[100:101], 0, s[4:5]
	s_mov_b64 s[4:5], 0x300000
	global_load_dwordx2 v[112:113], v[122:123], off offset:1024
	global_load_ushort v114, v[100:101], off offset:3584
	global_load_ushort v115, v[100:101], off offset:3648
	v_lshl_add_u64 v[102:103], v[102:103], 0, s[4:5]
	global_load_dwordx2 v[116:117], v[102:103], off
	s_or_b64 exec, exec, s[6:7]
	v_lshl_add_u64 v[16:17], v[16:17], 0, s[44:45]
	v_lshl_add_u64 v[6:7], v[6:7], 0, s[24:25]
	v_and_b32_e32 v33, 0xffff0000, v29
	v_and_b32_e32 v35, 0xffff0000, v28
	v_lshlrev_b32_e32 v32, 16, v29
	v_lshlrev_b32_e32 v34, 16, v28
	v_mov_b32_e32 v36, v33
	v_mov_b32_e32 v37, v35
	v_mov_b32_e32 v28, v32
	v_mov_b32_e32 v29, v34
	v_pk_mul_f32 v[36:37], v[36:37], v[36:37]
	v_and_b32_e32 v39, 0xffff0000, v26
	v_pk_fma_f32 v[28:29], v[28:29], v[28:29], v[36:37]
	v_and_b32_e32 v37, 0xffff0000, v27
	v_lshlrev_b32_e32 v36, 16, v27
	v_lshlrev_b32_e32 v38, 16, v26
	v_mov_b32_e32 v26, v39
	v_mov_b32_e32 v27, v37
	v_pk_mul_f32 v[26:27], v[26:27], v[26:27]
	v_mov_b32_e32 v40, v38
	v_mov_b32_e32 v41, v36
	v_and_b32_e32 v43, 0xffff0000, v31
	v_and_b32_e32 v45, 0xffff0000, v30
	v_pk_fma_f32 v[26:27], v[40:41], v[40:41], v[26:27]
	v_lshlrev_b32_e32 v42, 16, v31
	v_lshlrev_b32_e32 v44, 16, v30
	v_mov_b32_e32 v46, v45
	v_mov_b32_e32 v47, v43
	v_add_f32_e32 v26, v26, v27
	v_mov_b32_e32 v30, v44
	v_mov_b32_e32 v31, v42
	v_pk_mul_f32 v[46:47], v[46:47], v[46:47]
	v_pk_add_f32 v[26:27], v[28:29], v[26:27] op_sel_hi:[1,0]
	v_pk_fma_f32 v[30:31], v[30:31], v[30:31], v[46:47]
	v_mov_b32_e32 v47, v28
	v_mov_b32_e32 v46, v30
	v_mov_b32_e32 v26, v31
	v_pk_add_f32 v[26:27], v[46:47], v[26:27]
	s_nop 1
	v_add_f32_dpp v26, v26, v26 quad_perm:[1,0,3,2] row_mask:0xf bank_mask:0xf
	v_add_f32_dpp v27, v27, v27 quad_perm:[1,0,3,2] row_mask:0xf bank_mask:0xf
	v_lshl_add_u64 v[40:41], s[58:59], 0, v[14:15]
	s_nop 1
	v_add_f32_dpp v26, v26, v26 quad_perm:[2,3,0,1] row_mask:0xf bank_mask:0xf
	v_add_f32_dpp v27, v27, v27 quad_perm:[2,3,0,1] row_mask:0xf bank_mask:0xf
	s_nop 1
	v_add_f32_dpp v26, v26, v26 row_half_mirror row_mask:0xf bank_mask:0xf
	v_add_f32_dpp v27, v27, v27 row_half_mirror row_mask:0xf bank_mask:0xf
	s_nop 1
	v_add_f32_dpp v26, v26, v26 row_mirror row_mask:0xf bank_mask:0xf
	v_add_f32_dpp v27, v27, v27 row_mirror row_mask:0xf bank_mask:0xf
	v_mov_b32_e32 v28, v26
	v_mov_b32_e32 v29, v27
	s_nop 1
	v_permlane16_swap_b32_e32 v28, v26
	v_permlane16_swap_b32_e32 v29, v27
	v_pk_add_f32 v[26:27], v[26:27], v[28:29]
	v_mov_b32_e32 v28, v26
	v_mov_b32_e32 v29, v27
	s_nop 1
	v_permlane32_swap_b32_e32 v28, v26
	v_permlane32_swap_b32_e32 v29, v27
	v_pk_add_f32 v[26:27], v[26:27], v[28:29]
	s_waitcnt lgkmcnt(0)
	s_nop 0
	v_pk_fma_f32 v[30:31], v[26:27], s[52:53], v[18:19] op_sel_hi:[1,1,0]
	s_nop 0
	v_mul_f32_e32 v1, 0x4b800000, v31
	v_cmp_gt_f32_e64 s[38:39], s3, v31
	v_cmp_gt_f32_e32 vcc, s3, v30
	s_nop 0
	v_cndmask_b32_e64 v1, v31, v1, s[38:39]
	v_rsq_f32_e32 v1, v1
	s_nop 0
	v_mul_f32_e32 v25, 0x45800000, v1
	v_cndmask_b32_e64 v46, v1, v25, s[38:39]
	v_mul_f32_e32 v1, 0x4b800000, v30
	v_cndmask_b32_e32 v1, v30, v1, vcc
	v_rsq_f32_e32 v1, v1
	v_pk_mul_f32 v[26:27], v[46:47], v[38:39] op_sel_hi:[0,1]
	v_pk_mul_f32 v[28:29], v[46:47], v[36:37] op_sel_hi:[0,1]
	v_cvt_pk_bf16_f32 v26, v26, v27
	v_cvt_pk_bf16_f32 v27, v28, v29
	v_pk_mul_f32 v[28:29], v[46:47], v[34:35] op_sel_hi:[0,1]
	v_pk_mul_f32 v[32:33], v[46:47], v[32:33] op_sel_hi:[0,1]
	v_cvt_pk_bf16_f32 v28, v28, v29
	v_cvt_pk_bf16_f32 v29, v32, v33
	v_mul_f32_e32 v25, 0x45800000, v1
	global_store_dwordx4 v[40:41], v[26:29], off sc1
	s_nop 1
	v_cndmask_b32_e32 v26, v1, v25, vcc
	v_pk_mul_f32 v[28:29], v[26:27], v[44:45] op_sel_hi:[0,1]
	v_pk_mul_f32 v[26:27], v[26:27], v[42:43] op_sel_hi:[0,1]
	v_cvt_pk_bf16_f32 v28, v28, v29
	v_cvt_pk_bf16_f32 v29, v26, v27
	v_lshl_add_u64 v[26:27], s[58:59], 0, v[10:11]
	global_store_dwordx2 v[26:27], v[28:29], off sc1
	s_and_saveexec_b64 s[38:39], s[0:1]
	s_cbranch_execz .LBB0_299
	v_lshl_add_u64 v[28:29], s[58:59], 0, v[8:9]
	v_lshlrev_b32_e32 v1, 16, v104
	v_lshlrev_b32_e32 v25, 16, v105
	v_mov_b32_e32 v26, v106
	v_mov_b32_e32 v27, v107
	v_add_co_u32_e32 v28, vcc, 0x700000, v28
	v_mul_f32_e32 v30, v27, v25
	v_mul_f32_e32 v25, v26, v25
	v_fma_f32 v26, v26, v1, -v30
	v_fmac_f32_e32 v25, v27, v1
	v_bfe_u32 v1, v26, 16, 1
	v_addc_co_u32_e32 v29, vcc, 0, v29, vcc
	v_bfe_u32 v27, v25, 16, 1
	v_add3_u32 v1, v26, v1, s33
	v_add3_u32 v25, v25, v27, s33
	global_store_short_d16_hi v[28:29], v1, off
	global_store_short_d16_hi v[28:29], v25, off offset:64
	s_branch .LBB0_299

; __device__ __forceinline__ unsigned pk2(float lo, float hi) { return pg8::cvtpk(lo, hi); }
; __device__ __forceinline__ void gla_scan(const Params& P, int G) {
;     ...
;     if (threadIdx.x < 256) for (int gid = blockIdx.x * 256 + threadIdx.x; gid < 8 * 8192; gid += G * 256) {
;         const int bh = gid >> 13, e4 = gid & 8191, d = (4 * e4) & 127;
;         f32x4 st = {0.f, 0.f, 0.f, 0.f};
; #pragma unroll 16
;         for (int n = 0; n < 128; ++n) { const size_t unit = (size_t)bh * 128 + n;
;             const u32x2 w = *(const u32x2*)(DS + unit * 32768 + 4 * e4); const f32x4 dd = *(const f32x4*)(decay_g + unit * 128 + d);
;             u32x2 o; o.x = pk2(st[0], st[1]); o.y = pk2(st[2], st[3]); *(u32x2*)(ST + unit * 32768 + 4 * e4) = o;
;             f32x4 in; in[0] = __uint_as_float(w.x << 16); in[1] = __uint_as_float(w.x & 0xffff0000u); in[2] = __uint_as_float(w.y << 16); in[3] = __uint_as_float(w.y & 0xffff0000u);
;             st = dd * st + in; }
.LBB0_485:
	s_add_u32 s26, s58, 0x6800000
	s_addc_u32 s27, s59, 0
	global_load_dwordx2 v[26:27], v2, s[26:27]
	s_add_u32 s26, s58, 0x200000
	s_addc_u32 s27, s59, 0
	global_load_dwordx4 v[58:61], v0, s[26:27]
	s_add_u32 s26, s58, 0x6810000
	s_addc_u32 s27, s59, 0
	global_load_dwordx2 v[28:29], v2, s[26:27]
	s_add_u32 s26, s58, 0x200200
	s_addc_u32 s27, s59, 0
	global_load_dwordx4 v[62:65], v0, s[26:27]
	s_add_u32 s26, s58, 0x6820000
	s_addc_u32 s27, s59, 0
	global_load_dwordx2 v[30:31], v2, s[26:27]
	s_add_u32 s26, s58, 0x200400
	s_addc_u32 s27, s59, 0
	global_load_dwordx4 v[66:69], v0, s[26:27]
	s_add_u32 s26, s58, 0x6830000
	s_addc_u32 s27, s59, 0
	global_load_dwordx2 v[32:33], v2, s[26:27]
	s_add_u32 s26, s58, 0x200600
	s_addc_u32 s27, s59, 0
	global_load_dwordx4 v[70:73], v0, s[26:27]
	s_add_u32 s26, s58, 0x6840000
	s_addc_u32 s27, s59, 0
	global_load_dwordx2 v[34:35], v2, s[26:27]
	s_add_u32 s26, s58, 0x200800
	s_addc_u32 s27, s59, 0
	global_load_dwordx4 v[74:77], v0, s[26:27]
	s_add_u32 s26, s58, 0x6850000
	s_addc_u32 s27, s59, 0
	global_load_dwordx2 v[36:37], v2, s[26:27]
	s_add_u32 s26, s58, 0x200a00
	s_addc_u32 s27, s59, 0
	global_load_dwordx4 v[78:81], v0, s[26:27]
	s_add_u32 s26, s58, 0x6860000
	s_addc_u32 s27, s59, 0
	global_load_dwordx2 v[38:39], v2, s[26:27]
	s_add_u32 s26, s58, 0x200c00
	s_addc_u32 s27, s59, 0
	global_load_dwordx4 v[82:85], v0, s[26:27]
	s_add_u32 s26, s58, 0x6870000
	s_addc_u32 s27, s59, 0
	global_load_dwordx2 v[40:41], v2, s[26:27]
	s_add_u32 s26, s58, 0x200e00
	s_addc_u32 s27, s59, 0
	global_load_dwordx4 v[86:89], v0, s[26:27]
	s_add_u32 s26, s58, 0x6880000
	s_addc_u32 s27, s59, 0
	global_load_dwordx2 v[42:43], v2, s[26:27]
	s_add_u32 s26, s58, 0x201000
	s_addc_u32 s27, s59, 0
	global_load_dwordx4 v[90:93], v0, s[26:27]
	s_add_u32 s26, s58, 0x6890000
	s_addc_u32 s27, s59, 0
	global_load_dwordx2 v[44:45], v2, s[26:27]
	s_add_u32 s26, s58, 0x201200
	s_addc_u32 s27, s59, 0
	global_load_dwordx4 v[94:97], v0, s[26:27]
	s_add_u32 s26, s58, 0x68a0000
	s_addc_u32 s27, s59, 0
	global_load_dwordx2 v[46:47], v2, s[26:27]
	s_add_u32 s26, s58, 0x201400
	s_addc_u32 s27, s59, 0
	global_load_dwordx4 v[98:101], v0, s[26:27]
	s_add_u32 s26, s58, 0x68b0000
	s_addc_u32 s27, s59, 0
	global_load_dwordx2 v[48:49], v2, s[26:27]
	s_add_u32 s26, s58, 0x201600
	s_addc_u32 s27, s59, 0
	global_load_dwordx4 v[102:105], v0, s[26:27]
	s_add_u32 s26, s58, 0x68c0000
	s_addc_u32 s27, s59, 0
	global_load_dwordx2 v[50:51], v2, s[26:27]
	s_add_u32 s26, s58, 0x201800
	s_addc_u32 s27, s59, 0
	global_load_dwordx4 v[106:109], v0, s[26:27]
	s_add_u32 s26, s58, 0x68d0000
	s_addc_u32 s27, s59, 0
	global_load_dwordx2 v[52:53], v2, s[26:27]
	s_add_u32 s26, s58, 0x201a00
	s_addc_u32 s27, s59, 0
	global_load_dwordx4 v[110:113], v0, s[26:27]
	s_add_u32 s26, s58, 0x68e0000
	s_addc_u32 s27, s59, 0
	global_load_dwordx2 v[54:55], v2, s[26:27]
	s_add_u32 s26, s58, 0x201c00
	s_addc_u32 s27, s59, 0
	global_load_dwordx4 v[114:117], v0, s[26:27]
	s_add_u32 s26, s58, 0x68f0000
	s_addc_u32 s27, s59, 0
	global_load_dwordx2 v[56:57], v2, s[26:27]
	s_add_u32 s26, s58, 0x201e00
	s_addc_u32 s27, s59, 0
	global_load_dwordx4 v[118:121], v0, s[26:27]
	v_cvt_pk_bf16_f32 v22, v10, v11
	v_cvt_pk_bf16_f32 v23, v12, v13
	s_add_u32 s26, s58, 0x14800000
	s_addc_u32 s27, s59, 0
	global_store_dwordx2 v2, v[22:23], s[26:27] sc1
	s_waitcnt vmcnt(31)
	v_lshlrev_b32_e32 v16, 16, v26
	v_and_b32_e32 v17, 0xffff0000, v26
	v_lshlrev_b32_e32 v18, 16, v27
	v_and_b32_e32 v19, 0xffff0000, v27
	v_pk_fma_f32 v[10:11], v[10:11], v[58:59], v[16:17]
	v_pk_fma_f32 v[12:13], v[12:13], v[60:61], v[18:19]
	v_cvt_pk_bf16_f32 v22, v10, v11
	v_cvt_pk_bf16_f32 v23, v12, v13
	s_add_u32 s26, s58, 0x14810000
	s_addc_u32 s27, s59, 0
	global_store_dwordx2 v2, v[22:23], s[26:27] sc1
	s_waitcnt vmcnt(30)
	v_lshlrev_b32_e32 v16, 16, v28
	v_and_b32_e32 v17, 0xffff0000, v28
	v_lshlrev_b32_e32 v18, 16, v29
	v_and_b32_e32 v19, 0xffff0000, v29
	v_pk_fma_f32 v[10:11], v[10:11], v[62:63], v[16:17]
	v_pk_fma_f32 v[12:13], v[12:13], v[64:65], v[18:19]
	v_cvt_pk_bf16_f32 v22, v10, v11
	v_cvt_pk_bf16_f32 v23, v12, v13
	s_add_u32 s26, s58, 0x14820000
	s_addc_u32 s27, s59, 0
	global_store_dwordx2 v2, v[22:23], s[26:27] sc1
	s_waitcnt vmcnt(29)
	v_lshlrev_b32_e32 v16, 16, v30
	v_and_b32_e32 v17, 0xffff0000, v30
	v_lshlrev_b32_e32 v18, 16, v31
	v_and_b32_e32 v19, 0xffff0000, v31
	v_pk_fma_f32 v[10:11], v[10:11], v[66:67], v[16:17]
	v_pk_fma_f32 v[12:13], v[12:13], v[68:69], v[18:19]
	v_cvt_pk_bf16_f32 v22, v10, v11
	v_cvt_pk_bf16_f32 v23, v12, v13
	s_add_u32 s26, s58, 0x14830000
	s_addc_u32 s27, s59, 0
	global_store_dwordx2 v2, v[22:23], s[26:27] sc1
	s_waitcnt vmcnt(28)
	v_lshlrev_b32_e32 v16, 16, v32
	v_and_b32_e32 v17, 0xffff0000, v32
	v_lshlrev_b32_e32 v18, 16, v33
	v_and_b32_e32 v19, 0xffff0000, v33
	v_pk_fma_f32 v[10:11], v[10:11], v[70:71], v[16:17]
	v_pk_fma_f32 v[12:13], v[12:13], v[72:73], v[18:19]
	v_cvt_pk_bf16_f32 v22, v10, v11
	v_cvt_pk_bf16_f32 v23, v12, v13
	s_add_u32 s26, s58, 0x14840000
	s_addc_u32 s27, s59, 0
	global_store_dwordx2 v2, v[22:23], s[26:27] sc1
	s_waitcnt vmcnt(27)
; __device__ __forceinline__ unsigned pk2(float lo, float hi) { return pg8::cvtpk(lo, hi); }
; __device__ __forceinline__ void gla_scan(const Params& P, int G) {
;     ...
;     if (threadIdx.x < 256) for (int gid = blockIdx.x * 256 + threadIdx.x; gid < 8 * 8192; gid += G * 256) {
;         const int bh = gid >> 13, e4 = gid & 8191, d = (4 * e4) & 127;
;         f32x4 st = {0.f, 0.f, 0.f, 0.f};
; #pragma unroll 16
;         for (int n = 0; n < 128; ++n) { const size_t unit = (size_t)bh * 128 + n;
;             const u32x2 w = *(const u32x2*)(DS + unit * 32768 + 4 * e4); const f32x4 dd = *(const f32x4*)(decay_g + unit * 128 + d);
;             u32x2 o; o.x = pk2(st[0], st[1]); o.y = pk2(st[2], st[3]); *(u32x2*)(ST + unit * 32768 + 4 * e4) = o;
;             f32x4 in; in[0] = __uint_as_float(w.x << 16); in[1] = __uint_as_float(w.x & 0xffff0000u); in[2] = __uint_as_float(w.y << 16); in[3] = __uint_as_float(w.y & 0xffff0000u);
;             st = dd * st + in; }
	v_lshlrev_b32_e32 v16, 16, v34
	v_and_b32_e32 v17, 0xffff0000, v34
	v_lshlrev_b32_e32 v18, 16, v35
	v_and_b32_e32 v19, 0xffff0000, v35
	v_pk_fma_f32 v[10:11], v[10:11], v[74:75], v[16:17]
	v_pk_fma_f32 v[12:13], v[12:13], v[76:77], v[18:19]
	v_cvt_pk_bf16_f32 v22, v10, v11
	v_cvt_pk_bf16_f32 v23, v12, v13
	s_add_u32 s26, s58, 0x14850000
	s_addc_u32 s27, s59, 0
	global_store_dwordx2 v2, v[22:23], s[26:27] sc1
	s_waitcnt vmcnt(26)
	v_lshlrev_b32_e32 v16, 16, v36
	v_and_b32_e32 v17, 0xffff0000, v36
	v_lshlrev_b32_e32 v18, 16, v37
	v_and_b32_e32 v19, 0xffff0000, v37
	v_pk_fma_f32 v[10:11], v[10:11], v[78:79], v[16:17]
	v_pk_fma_f32 v[12:13], v[12:13], v[80:81], v[18:19]
	v_cvt_pk_bf16_f32 v22, v10, v11
	v_cvt_pk_bf16_f32 v23, v12, v13
	s_add_u32 s26, s58, 0x14860000
	s_addc_u32 s27, s59, 0
	global_store_dwordx2 v2, v[22:23], s[26:27] sc1
	s_waitcnt vmcnt(25)
	v_lshlrev_b32_e32 v16, 16, v38
	v_and_b32_e32 v17, 0xffff0000, v38
	v_lshlrev_b32_e32 v18, 16, v39
	v_and_b32_e32 v19, 0xffff0000, v39
	v_pk_fma_f32 v[10:11], v[10:11], v[82:83], v[16:17]
	v_pk_fma_f32 v[12:13], v[12:13], v[84:85], v[18:19]
	v_cvt_pk_bf16_f32 v22, v10, v11
	v_cvt_pk_bf16_f32 v23, v12, v13
	s_add_u32 s26, s58, 0x14870000
	s_addc_u32 s27, s59, 0
	global_store_dwordx2 v2, v[22:23], s[26:27] sc1
	s_waitcnt vmcnt(24)
	v_lshlrev_b32_e32 v16, 16, v40
	v_and_b32_e32 v17, 0xffff0000, v40
	v_lshlrev_b32_e32 v18, 16, v41
	v_and_b32_e32 v19, 0xffff0000, v41
	v_pk_fma_f32 v[10:11], v[10:11], v[86:87], v[16:17]
	v_pk_fma_f32 v[12:13], v[12:13], v[88:89], v[18:19]
	v_cvt_pk_bf16_f32 v22, v10, v11
	v_cvt_pk_bf16_f32 v23, v12, v13
	s_add_u32 s26, s58, 0x14880000
	s_addc_u32 s27, s59, 0
	global_store_dwordx2 v2, v[22:23], s[26:27] sc1
	s_waitcnt vmcnt(23)
	v_lshlrev_b32_e32 v16, 16, v42
	v_and_b32_e32 v17, 0xffff0000, v42
	v_lshlrev_b32_e32 v18, 16, v43
	v_and_b32_e32 v19, 0xffff0000, v43
	v_pk_fma_f32 v[10:11], v[10:11], v[90:91], v[16:17]
	v_pk_fma_f32 v[12:13], v[12:13], v[92:93], v[18:19]
	v_cvt_pk_bf16_f32 v22, v10, v11
	v_cvt_pk_bf16_f32 v23, v12, v13
	s_add_u32 s26, s58, 0x14890000
	s_addc_u32 s27, s59, 0
	global_store_dwordx2 v2, v[22:23], s[26:27] sc1
	s_waitcnt vmcnt(22)
	v_lshlrev_b32_e32 v16, 16, v44
	v_and_b32_e32 v17, 0xffff0000, v44
	v_lshlrev_b32_e32 v18, 16, v45
	v_and_b32_e32 v19, 0xffff0000, v45
	v_pk_fma_f32 v[10:11], v[10:11], v[94:95], v[16:17]
	v_pk_fma_f32 v[12:13], v[12:13], v[96:97], v[18:19]
	v_cvt_pk_bf16_f32 v22, v10, v11
	v_cvt_pk_bf16_f32 v23, v12, v13
	s_add_u32 s26, s58, 0x148a0000
	s_addc_u32 s27, s59, 0
	global_store_dwordx2 v2, v[22:23], s[26:27] sc1
	s_waitcnt vmcnt(21)
	v_lshlrev_b32_e32 v16, 16, v46
	v_and_b32_e32 v17, 0xffff0000, v46
	v_lshlrev_b32_e32 v18, 16, v47
	v_and_b32_e32 v19, 0xffff0000, v47
	v_pk_fma_f32 v[10:11], v[10:11], v[98:99], v[16:17]
	v_pk_fma_f32 v[12:13], v[12:13], v[100:101], v[18:19]
	v_cvt_pk_bf16_f32 v22, v10, v11
	v_cvt_pk_bf16_f32 v23, v12, v13
	s_add_u32 s26, s58, 0x148b0000
	s_addc_u32 s27, s59, 0
	global_store_dwordx2 v2, v[22:23], s[26:27] sc1
	s_waitcnt vmcnt(20)
	v_lshlrev_b32_e32 v16, 16, v48
	v_and_b32_e32 v17, 0xffff0000, v48
	v_lshlrev_b32_e32 v18, 16, v49
	v_and_b32_e32 v19, 0xffff0000, v49
	v_pk_fma_f32 v[10:11], v[10:11], v[102:103], v[16:17]
	v_pk_fma_f32 v[12:13], v[12:13], v[104:105], v[18:19]
	v_cvt_pk_bf16_f32 v22, v10, v11
	v_cvt_pk_bf16_f32 v23, v12, v13
	s_add_u32 s26, s58, 0x148c0000
	s_addc_u32 s27, s59, 0
	global_store_dwordx2 v2, v[22:23], s[26:27] sc1
	s_waitcnt vmcnt(19)
	v_lshlrev_b32_e32 v16, 16, v50
	v_and_b32_e32 v17, 0xffff0000, v50
	v_lshlrev_b32_e32 v18, 16, v51
	v_and_b32_e32 v19, 0xffff0000, v51
	v_pk_fma_f32 v[10:11], v[10:11], v[106:107], v[16:17]
	v_pk_fma_f32 v[12:13], v[12:13], v[108:109], v[18:19]
	v_cvt_pk_bf16_f32 v22, v10, v11
	v_cvt_pk_bf16_f32 v23, v12, v13
	s_add_u32 s26, s58, 0x148d0000
	s_addc_u32 s27, s59, 0
	global_store_dwordx2 v2, v[22:23], s[26:27] sc1
	s_waitcnt vmcnt(18)
	v_lshlrev_b32_e32 v16, 16, v52
	v_and_b32_e32 v17, 0xffff0000, v52
	v_lshlrev_b32_e32 v18, 16, v53
	v_and_b32_e32 v19, 0xffff0000, v53
	v_pk_fma_f32 v[10:11], v[10:11], v[110:111], v[16:17]
	v_pk_fma_f32 v[12:13], v[12:13], v[112:113], v[18:19]
	v_cvt_pk_bf16_f32 v22, v10, v11
	v_cvt_pk_bf16_f32 v23, v12, v13
	s_add_u32 s26, s58, 0x148e0000
	s_addc_u32 s27, s59, 0
	global_store_dwordx2 v2, v[22:23], s[26:27] sc1
	s_waitcnt vmcnt(17)
	v_lshlrev_b32_e32 v16, 16, v54
	v_and_b32_e32 v17, 0xffff0000, v54
	v_lshlrev_b32_e32 v18, 16, v55
	v_and_b32_e32 v19, 0xffff0000, v55
	v_pk_fma_f32 v[10:11], v[10:11], v[114:115], v[16:17]
	v_pk_fma_f32 v[12:13], v[12:13], v[116:117], v[18:19]
	v_cvt_pk_bf16_f32 v22, v10, v11
	v_cvt_pk_bf16_f32 v23, v12, v13
	s_add_u32 s26, s58, 0x148f0000
	s_addc_u32 s27, s59, 0
	global_store_dwordx2 v2, v[22:23], s[26:27] sc1
	s_waitcnt vmcnt(16)
	v_lshlrev_b32_e32 v16, 16, v56
	v_and_b32_e32 v17, 0xffff0000, v56
	v_lshlrev_b32_e32 v18, 16, v57
	v_and_b32_e32 v19, 0xffff0000, v57
	v_pk_fma_f32 v[10:11], v[10:11], v[118:119], v[16:17]
	v_pk_fma_f32 v[12:13], v[12:13], v[120:121], v[18:19]
	s_mov_b64 s[26:27], 0x2000
	v_lshl_add_u64 v[0:1], v[0:1], 0, s[26:27]
	s_mov_b64 s[26:27], 0x100000
	v_lshl_add_u64 v[2:3], v[2:3], 0, s[26:27]
	s_add_i32 s23, s23, -16
	s_cmp_eq_u32 s23, 0
	s_cbranch_scc0 .LBB0_485
	v_add_u32_e32 v14, s3, v14
	s_mov_b32 s23, 0xffff
	v_cmp_lt_i32_e32 vcc, s23, v14
	s_or_b64 s[36:37], vcc, s[36:37]
	v_add_u32_e32 v15, s22, v15
	s_andn2_b64 exec, exec, s[36:37]
	s_cbranch_execnz .LBB0_484

; __device__ __forceinline__ unsigned pk2(float lo, float hi) { return pg8::cvtpk(lo, hi); }
; __device__ __forceinline__ void attn_unit(const Params& P, LAS unsigned char* lds, int bh, int qb) {
;     ...
; #pragma unroll
;     for (int qk = 0; qk < 2; ++qk) { const float rl = 1.0f / lacc[qk][0];
;         bf16_t* op = AO + (rowb + q0 + 16 * qk + fr) * DM + 128 * h + 4 * fq;
; #pragma unroll
;         for (int dvb = 0; dvb < 8; ++dvb) { u32x2 w; w.x = pk2(o[dvb][qk][0] * rl, o[dvb][qk][1] * rl); w.y = pk2(o[dvb][qk][2] * rl, o[dvb][qk][3] * rl); *(u32x2*)(op + 16 * dvb) = w; } }
.LBB0_551:
	v_div_scale_f32 v2, s[0:1], v112, v112, 1.0
	v_rcp_f32_e32 v3, v2
	v_lshlrev_b32_e32 v172, 1, v215
	v_lshl_add_u64 v[0:1], s[86:87], 0, v[172:173]
	v_fma_f32 v4, -v2, v3, 1.0
	v_fmac_f32_e32 v3, v4, v3
	v_div_scale_f32 v4, vcc, 1.0, v112, 1.0
	v_mul_f32_e32 v5, v4, v3
	v_fma_f32 v6, -v2, v5, v4
	v_fmac_f32_e32 v5, v6, v3
	v_fma_f32 v2, -v2, v5, v4
	v_div_fmas_f32 v2, v2, v3, v5
	v_div_fixup_f32 v2, v2, v112, 1.0
	v_lshlrev_b64 v[4:5], 12, v[174:175]
	v_pk_mul_f32 v[8:9], v[2:3], v[116:117] op_sel_hi:[0,1]
	v_pk_mul_f32 v[10:11], v[2:3], v[118:119] op_sel_hi:[0,1]
	v_lshl_add_u64 v[6:7], v[0:1], 0, v[4:5]
	v_cvt_pk_bf16_f32 v8, v8, v9
	v_cvt_pk_bf16_f32 v9, v10, v11
	global_store_dwordx2 v[6:7], v[8:9], off sc1
	v_pk_mul_f32 v[8:9], v[2:3], v[108:109] op_sel_hi:[0,1]
	v_pk_mul_f32 v[10:11], v[2:3], v[110:111] op_sel_hi:[0,1]
	v_cvt_pk_bf16_f32 v8, v8, v9
	v_cvt_pk_bf16_f32 v9, v10, v11
	global_store_dwordx2 v[6:7], v[8:9], off offset:32 sc1
	v_pk_mul_f32 v[8:9], v[2:3], v[104:105] op_sel_hi:[0,1]
	v_pk_mul_f32 v[10:11], v[2:3], v[106:107] op_sel_hi:[0,1]
	v_cvt_pk_bf16_f32 v8, v8, v9
	v_cvt_pk_bf16_f32 v9, v10, v11
	global_store_dwordx2 v[6:7], v[8:9], off offset:64 sc1
	v_pk_mul_f32 v[8:9], v[2:3], v[100:101] op_sel_hi:[0,1]
	v_pk_mul_f32 v[10:11], v[2:3], v[102:103] op_sel_hi:[0,1]
	v_cvt_pk_bf16_f32 v8, v8, v9
	v_cvt_pk_bf16_f32 v9, v10, v11
	global_store_dwordx2 v[6:7], v[8:9], off offset:96 sc1
	v_pk_mul_f32 v[8:9], v[2:3], v[96:97] op_sel_hi:[0,1]
	v_pk_mul_f32 v[10:11], v[2:3], v[98:99] op_sel_hi:[0,1]
	v_cvt_pk_bf16_f32 v8, v8, v9
	v_cvt_pk_bf16_f32 v9, v10, v11
	global_store_dwordx2 v[6:7], v[8:9], off offset:128 sc1
	v_pk_mul_f32 v[8:9], v[2:3], v[92:93] op_sel_hi:[0,1]
	v_pk_mul_f32 v[10:11], v[2:3], v[94:95] op_sel_hi:[0,1]
	v_cvt_pk_bf16_f32 v8, v8, v9
	v_cvt_pk_bf16_f32 v9, v10, v11
	global_store_dwordx2 v[6:7], v[8:9], off offset:160 sc1
	v_pk_mul_f32 v[8:9], v[2:3], v[88:89] op_sel_hi:[0,1]
	v_pk_mul_f32 v[10:11], v[2:3], v[90:91] op_sel_hi:[0,1]
	v_cvt_pk_bf16_f32 v8, v8, v9
	v_cvt_pk_bf16_f32 v9, v10, v11
	v_div_scale_f32 v10, s[0:1], v76, v76, 1.0
	v_rcp_f32_e32 v11, v10
	global_store_dwordx2 v[6:7], v[8:9], off offset:192 sc1
	v_pk_mul_f32 v[8:9], v[2:3], v[72:73] op_sel_hi:[0,1]
	v_pk_mul_f32 v[2:3], v[2:3], v[74:75] op_sel_hi:[0,1]
	v_cvt_pk_bf16_f32 v8, v8, v9
	v_cvt_pk_bf16_f32 v9, v2, v3
	v_fma_f32 v2, -v10, v11, 1.0
	v_fmac_f32_e32 v11, v2, v11
	v_div_scale_f32 v2, vcc, 1.0, v76, 1.0
	v_mul_f32_e32 v3, v2, v11
	global_store_dwordx2 v[6:7], v[8:9], off offset:224 sc1
	v_fma_f32 v6, -v10, v3, v2
	v_fmac_f32_e32 v3, v6, v11
	v_fma_f32 v2, -v10, v3, v2
	v_div_fmas_f32 v2, v2, v11, v3
	v_div_fixup_f32 v2, v2, v76, 1.0
	v_or_b32_e32 v4, 0x10000, v4
	v_lshl_add_u64 v[0:1], v[0:1], 0, v[4:5]
	v_pk_mul_f32 v[4:5], v[2:3], v[84:85] op_sel_hi:[0,1]
	v_pk_mul_f32 v[6:7], v[2:3], v[86:87] op_sel_hi:[0,1]
	v_cvt_pk_bf16_f32 v4, v4, v5
	v_cvt_pk_bf16_f32 v5, v6, v7
	global_store_dwordx2 v[0:1], v[4:5], off sc1
	v_pk_mul_f32 v[4:5], v[2:3], v[80:81] op_sel_hi:[0,1]
	v_pk_mul_f32 v[6:7], v[2:3], v[82:83] op_sel_hi:[0,1]
	v_cvt_pk_bf16_f32 v4, v4, v5
	v_cvt_pk_bf16_f32 v5, v6, v7
	global_store_dwordx2 v[0:1], v[4:5], off offset:32 sc1
	v_pk_mul_f32 v[4:5], v[2:3], v[68:69] op_sel_hi:[0,1]
	v_pk_mul_f32 v[6:7], v[2:3], v[70:71] op_sel_hi:[0,1]
	v_cvt_pk_bf16_f32 v4, v4, v5
	v_cvt_pk_bf16_f32 v5, v6, v7
	global_store_dwordx2 v[0:1], v[4:5], off offset:64 sc1
	v_pk_mul_f32 v[4:5], v[2:3], v[64:65] op_sel_hi:[0,1]
	v_pk_mul_f32 v[6:7], v[2:3], v[66:67] op_sel_hi:[0,1]
	v_cvt_pk_bf16_f32 v4, v4, v5
	v_cvt_pk_bf16_f32 v5, v6, v7
	global_store_dwordx2 v[0:1], v[4:5], off offset:96 sc1
	v_pk_mul_f32 v[4:5], v[2:3], v[60:61] op_sel_hi:[0,1]
	v_pk_mul_f32 v[6:7], v[2:3], v[62:63] op_sel_hi:[0,1]
	v_cvt_pk_bf16_f32 v4, v4, v5
	v_cvt_pk_bf16_f32 v5, v6, v7
	global_store_dwordx2 v[0:1], v[4:5], off offset:128 sc1
	v_pk_mul_f32 v[4:5], v[2:3], v[56:57] op_sel_hi:[0,1]
	v_pk_mul_f32 v[6:7], v[2:3], v[58:59] op_sel_hi:[0,1]
	v_cvt_pk_bf16_f32 v4, v4, v5
	v_cvt_pk_bf16_f32 v5, v6, v7
	global_store_dwordx2 v[0:1], v[4:5], off offset:160 sc1
	v_pk_mul_f32 v[4:5], v[2:3], v[52:53] op_sel_hi:[0,1]
	v_pk_mul_f32 v[6:7], v[2:3], v[54:55] op_sel_hi:[0,1]
	v_cvt_pk_bf16_f32 v4, v4, v5
	v_cvt_pk_bf16_f32 v5, v6, v7
	global_store_dwordx2 v[0:1], v[4:5], off offset:192 sc1
	v_pk_mul_f32 v[4:5], v[2:3], v[48:49] op_sel_hi:[0,1]
	v_pk_mul_f32 v[2:3], v[2:3], v[50:51] op_sel_hi:[0,1]
	v_cvt_pk_bf16_f32 v4, v4, v5
	v_cvt_pk_bf16_f32 v5, v2, v3
	s_mov_b64 s[0:1], 0
	s_and_b64 vcc, exec, s[64:65]
	global_store_dwordx2 v[0:1], v[4:5], off offset:224 sc1
	s_cbranch_vccnz .LBB0_549
